# P1 start staggered by (bx>>6) x 2.2 us within each row-panel group so epilogue store bursts do not coincide
# baseline (speedup 1.0000x reference)
; #define PG8_WAIT_V(n) asm volatile("s_waitcnt vmcnt(" #n ")" ::: "memory")
; #define PG8_BAR __builtin_amdgcn_s_barrier()
; template <class Epi, class Sched, bool ALIGN_EPI = false, bool SP2 = false, bool SPLITK = false>
; __device__ __forceinline__ void gemm_phase(PG8_LAS unsigned char* lds, const Gemm g, const Sched& S, const Epi& E) {
;     ...
;         if (wr == 1) PG8_BAR;
;         PG8_WAIT_V(8); PG8_BAR;
;         PG8_WAIT_V(6); PG8_BAR;
.LBB0_155:
	s_cmp_lg_u32 s98, 0
	s_cbranch_scc0 .Lstag_done
	s_lshr_b32 vcc_lo, s1, 6
	s_cmp_eq_u32 vcc_lo, 0
	s_cbranch_scc1 .Lstag_done
.Lstag_loop:
	s_sleep 69
	s_sub_u32 vcc_lo, vcc_lo, 1
	s_cmp_lg_u32 vcc_lo, 0
	s_cbranch_scc1 .Lstag_loop
